# v20 + S5 phase: half of each XCD's CUs start S5 one s_sleep 127 later (stagger memory bursts of the short-K GEMMs)
# speedup vs baseline: 1.0055x; 1.0055x over previous
; #define PG8_STAGE(bufoff, gbase, voff) do { _Pragma("unroll") for (int _i = 0; _i < 2; ++_i) \
;         __builtin_amdgcn_global_load_lds((const unsigned*)((const char*)(gbase) + (voff)[_i]), (PG8_LAS unsigned*)(lds + (bufoff) + ldsw + _i * 8192), 16, 0, 0); } while (0)
; #define PG8_WAIT_V(n) asm volatile("s_waitcnt vmcnt(" #n ")" ::: "memory")
; #define PG8_BAR __builtin_amdgcn_s_barrier()
; template <class Epi, class Sched, bool ALIGN_EPI = false, bool SP2 = false>
; __device__ __forceinline__ void gemm_phase(PG8_LAS unsigned char* lds, const Gemm g, const Sched& S, const Epi& E, const int tid) {
;     ...
;     const char* cA = (const char*)g.A + (size_t)cur.pm * 2 * hstepA; const char* cB = (const char*)g.Bt + ((size_t)(cur.pm / g.grp_tiles) * g.grp_brows + (size_t)cur.pn * BM) * g.ldb * 2;
;     S.a_ready(cur);
;     if constexpr (SP2) {
;         PG8_STAGE(PG8_SB(0, 0), cB, voffB); PG8_STAGE(PG8_SB(0, 1), cB + hstepB, voffB); PG8_STAGE(PG8_SA(0, 0), cA, voffA); PG8_STAGE(PG8_SA(0, 1), cA + hstepA, voffA);
;         if (wr == 1) PG8_BAR;
;         PG8_WAIT_V(2); PG8_BAR;
;         PG8_STAGE(PG8_SB(1, 0), cB + kstep, voffB); PG8_STAGE(PG8_SA(1, 0), cA + kstep, voffA); PG8_STAGE(PG8_SB(1, 1), cB + hstepB + kstep, voffB);
;         PG8_WAIT_V(6); PG8_BAR;
;     } else {
;         PG8_STAGE(PG8_SB(0, 0), cB, voffB); PG8_STAGE(PG8_SA(0, 0), cA, voffA); PG8_STAGE(PG8_SB(0, 1), cB + hstepB, voffB); PG8_STAGE(PG8_SA(0, 1), cA + hstepA, voffA);
;         if (wr == 1) PG8_BAR;
;         PG8_WAIT_V(4); PG8_BAR;
;         PG8_STAGE(PG8_SB(1, 0), cB + kstep, voffB); PG8_STAGE(PG8_SA(1, 0), cA + kstep, voffA); PG8_STAGE(PG8_SB(1, 1), cB + hstepB + kstep, voffB);
;         PG8_WAIT_V(6); PG8_BAR;
; __global__ void __launch_bounds__(NWAVES * 64, 2) fwd_kernel(Args args) {
;     ...
;         {
;             PHASE_BEGIN();
;             pg8::Gemm g{WSP(const bf16, WS_A2), WSP(const bf16, WS_S5W + (size_t)l * S5W_LAYER), 64 * 2048, 256, 256, pg8::A2_LD, 256, 8, 128};
;             pg8::StaticOrder S; S.init(64 * 2048, 256, G, bx);
;             pg8::EpiS5P1 Ep{ws};
;             pg8::gemm_phase<pg8::EpiS5P1, pg8::StaticOrder, true, true>(L, g, S, Ep, tidp);
.LBB0_266:
	s_or_b64 exec, exec, s[36:37]
	s_bitcmp1_b32 s2, 3
	s_cbranch_scc0 .Lxs_s5go
	s_sleep 127
.Lxs_s5go:
	v_mov_b32_e32 v0, v205
	s_mov_b32 s0, s2
	v_readlane_b32 s1, v255, 0
	v_mov_b32_e32 v2, v205
	s_waitcnt lgkmcnt(0)
	s_barrier
	v_readlane_b32 s6, v255, 8
	v_add_u32_e32 v2, 0, v2
	v_add_u32_e32 v2, 0x200c8, v2
	ds_read_b64 v[2:3], v2
	v_mbcnt_lo_u32_b32 v0, -1, v0
	v_mbcnt_hi_u32_b32 v0, -1, v0
	v_lshl_add_u32 v1, s1, 6, v0
	v_readlane_b32 s0, v255, 51
	v_readlane_b32 s7, v255, 9
	s_waitcnt lgkmcnt(0)
	v_readfirstlane_b32 s12, v2
	v_readlane_b32 s1, v255, 52
	v_cndmask_b32_e64 v2, 0, 1, s[6:7]
	v_readfirstlane_b32 s13, v3
	s_lshl_b64 s[8:9], s[0:1], 24
	v_readfirstlane_b32 s0, v1
	v_cmp_ne_u32_e64 s[4:5], 1, v2
	s_andn2_b64 vcc, exec, s[6:7]
	s_cbranch_vccnz .LBB0_288
	v_lshlrev_b32_e32 v2, 4, v1
	v_add_u32_e32 v3, 0x2000, v2
	v_ashrrev_i32_e32 v4, 31, v3
	v_lshrrev_b32_e32 v4, 22, v4
	v_add_u32_e32 v4, v3, v4
	v_ashrrev_i32_e32 v4, 10, v4
	v_mul_i32_i24_e32 v5, 0x400, v4
	v_sub_u32_e32 v3, v3, v5
	v_lshrrev_b32_e32 v5, 4, v3
	v_bitop3_b32 v3, v5, v3, 32 bitop3:0x6c
	v_ashrrev_i32_e32 v5, 31, v3
	v_lshrrev_b32_e32 v5, 26, v5
	s_add_u32 s28, s12, 0x15a00000
	v_add_u32_e32 v5, v3, v5
	v_lshlrev_b32_e32 v7, 3, v4
	s_addc_u32 s29, s13, 0
	v_ashrrev_i32_e32 v6, 6, v5
	v_and_b32_e32 v7, -16, v7
	v_and_b32_e32 v5, 0xc0, v5
	s_add_u32 s1, s12, s8
	v_add_u32_e32 v7, v6, v7
	v_lshlrev_b32_e32 v4, 5, v4
	v_sub_u32_e32 v3, v3, v5
	s_addc_u32 s6, s13, s9
	v_and_b32_e32 v6, 3, v6
	s_mov_b32 s7, 0x7fffe0
	v_lshrrev_b32_e32 v8, 2, v7
	v_lshlrev_b32_e32 v9, 1, v7
	v_and_b32_e32 v4, 32, v4
	v_ashrrev_i16_sdwa v3, v254, sext(v3) dst_sel:DWORD dst_unused:UNUSED_PAD src0_sel:DWORD src1_sel:BYTE_0
	s_add_u32 s30, s1, 0xa00000
	v_and_or_b32 v6, v7, s7, v6
	v_and_b32_e32 v8, 4, v8
	v_and_b32_e32 v9, 24, v9
	v_add_u32_sdwa v3, v4, sext(v3) dst_sel:DWORD dst_unused:UNUSED_PAD src0_sel:DWORD src1_sel:WORD_0
	s_addc_u32 s31, s6, 0
	v_or3_b32 v6, v6, v8, v9
	v_lshlrev_b32_e32 v4, 1, v3
	s_movk_i32 s6, 0x180
	v_lshl_add_u32 v64, v6, 9, v4
	v_mul_lo_u32 v4, v7, s6
	v_add_lshl_u32 v66, v3, v4, 1
	v_bfe_i32 v3, v1, 27, 1
	v_lshrrev_b32_e32 v3, 22, v3
	v_add_u32_e32 v3, v2, v3
	v_and_b32_e32 v3, 0xfffffc00, v3
	v_sub_u32_e32 v2, v2, v3
	v_lshrrev_b32_e32 v3, 4, v2
	v_ashrrev_i32_e32 v5, 31, v1
	v_bitop3_b32 v2, v3, v2, 32 bitop3:0x6c
	v_lshrrev_b32_e32 v5, 26, v5
	v_ashrrev_i32_e32 v3, 31, v2
	v_add_u32_e32 v1, v1, v5
	v_lshrrev_b32_e32 v3, 26, v3
	v_ashrrev_i32_e32 v1, 6, v1
	v_add_u32_e32 v3, v2, v3
	v_lshlrev_b32_e32 v5, 3, v1
	v_ashrrev_i32_e32 v4, 6, v3
	v_and_b32_e32 v5, -16, v5
	v_and_b32_e32 v3, 0xc0, v3
	v_add_u32_e32 v5, v4, v5
	v_lshlrev_b32_e32 v1, 5, v1
	v_sub_u32_e32 v2, v2, v3
	v_and_b32_e32 v4, 3, v4
	v_lshrrev_b32_e32 v6, 2, v5
	v_lshlrev_b32_e32 v7, 1, v5
	v_and_b32_e32 v1, 32, v1
	v_ashrrev_i16_sdwa v2, v254, sext(v2) dst_sel:DWORD dst_unused:UNUSED_PAD src0_sel:DWORD src1_sel:BYTE_0
	v_and_or_b32 v4, v5, s7, v4
	v_and_b32_e32 v6, 4, v6
	v_and_b32_e32 v7, 24, v7
	v_add_u32_sdwa v1, v1, sext(v2) dst_sel:DWORD dst_unused:UNUSED_PAD src0_sel:DWORD src1_sel:WORD_0
	s_ashr_i32 s1, s0, 6
	v_or3_b32 v4, v4, v6, v7
	v_lshlrev_b32_e32 v2, 1, v1
	s_ashr_i32 s34, s0, 8
	s_lshl_b32 s35, s1, 10
	v_lshl_add_u32 v204, v4, 9, v2
	v_mul_lo_u32 v2, v5, s6
	v_readlane_b32 s6, v255, 13
	v_readlane_b32 s7, v255, 14
	s_add_u32 s26, s30, s6
	s_addc_u32 s27, s31, s7
	s_add_i32 s36, s35, 0
	s_add_i32 m0, s36, 0x10000
	v_add_lshl_u32 v68, v1, v2, 1
	global_load_lds_dwordx4 v204, s[26:27]
	s_add_i32 m0, s36, 0x12000
	s_add_u32 s6, s26, 0x10000
	s_addc_u32 s7, s27, 0
	s_add_i32 s37, s36, 0x14000
	global_load_lds_dwordx4 v64, s[26:27]
	s_mov_b32 m0, s37
	s_add_i32 s42, s36, 0x16000
	global_load_lds_dwordx4 v204, s[6:7]
	s_mov_b32 m0, s42
	s_nop 0
	global_load_lds_dwordx4 v64, s[6:7]
	v_readlane_b32 s6, v255, 22
	s_add_u32 s24, s28, s6
	v_readlane_b32 s6, v255, 20
	s_addc_u32 s25, s29, s6
	s_add_i32 s43, s36, 0x2000
	s_mov_b32 m0, s36
	s_add_u32 s6, s24, 0x18000
	global_load_lds_dwordx4 v68, s[24:25]
	s_mov_b32 m0, s43
	s_addc_u32 s7, s25, 0
	s_add_i32 s46, s36, 0x4000
	global_load_lds_dwordx4 v66, s[24:25]
	s_mov_b32 m0, s46
	s_add_i32 s47, s36, 0x6000
	global_load_lds_dwordx4 v68, s[6:7]
	s_mov_b32 m0, s47
	s_cmp_eq_u32 s34, 1
	global_load_lds_dwordx4 v66, s[6:7]
	s_cselect_b64 s[14:15], -1, 0
	s_cmp_lg_u32 s34, 1
	s_cbranch_scc1 .LBB0_269
	s_barrier
